# plus sample-group conv item hand-written; hipcc item loop left with one RWKV sample step per workgroup
# speedup vs baseline: 1.0185x; 1.0053x over previous
.Lcv_n_240:
	s_add_u32 s6, s6, 0x1000
	s_addc_u32 s7, s7, 0
	global_load_dwordx2 v[92:93], v16, s[6:7]
	s_add_u32 s6, s6, 0x1000
	s_addc_u32 s7, s7, 0
	global_load_dwordx2 v[94:95], v16, s[6:7]
	s_add_u32 s6, s6, 0x1000
	s_addc_u32 s7, s7, 0
	global_load_dwordx2 v[96:97], v16, s[6:7]
	s_add_u32 s6, s6, 0x1000
	s_addc_u32 s7, s7, 0
	global_load_dwordx2 v[98:99], v16, s[6:7]
	s_add_u32 s6, s6, 0x1000
	s_addc_u32 s7, s7, 0
	global_load_dwordx2 v[100:101], v16, s[6:7]
	s_add_u32 s6, s6, 0x1000
	s_addc_u32 s7, s7, 0
	global_load_dwordx2 v[102:103], v16, s[6:7]
	s_add_u32 s6, s6, 0x1000
	s_addc_u32 s7, s7, 0
	global_load_dwordx2 v[104:105], v16, s[6:7]
	s_add_u32 s6, s6, 0x1000
	s_addc_u32 s7, s7, 0
	global_load_dwordx2 v[106:107], v16, s[6:7]
	s_add_u32 s6, s6, 0x1000
	s_addc_u32 s7, s7, 0
	s_add_u32 s66, s66, 0x800000
	s_addc_u32 s67, s67, 0
	ds_read_b128 v[8:11], v17 offset:0
	ds_read_b128 v[12:15], v17 offset:1024
	ds_read_b128 v[20:23], v17 offset:2048
	ds_read_b128 v[24:27], v17 offset:3072
	s_waitcnt lgkmcnt(0)
	s_barrier
	v_pk_add_f32 v[108:109], v[8:9], v[10:11]
	v_pk_add_f32 v[108:109], v[108:109], v[12:13]
	v_pk_add_f32 v[108:109], v[108:109], v[14:15]
	v_pk_add_f32 v[108:109], v[108:109], v[20:21]
	v_pk_add_f32 v[108:109], v[108:109], v[22:23]
	v_pk_add_f32 v[108:109], v[108:109], v[24:25]
	v_pk_add_f32 v[108:109], v[108:109], v[26:27]
	v_add_f32_e32 v108, v108, v109
	s_nop 1
	v_add_f32_dpp v108, v108, v108 quad_perm:[1,0,3,2] row_mask:0xf bank_mask:0xf bound_ctrl:1
	s_nop 1
	v_add_f32_dpp v108, v108, v108 quad_perm:[2,3,0,1] row_mask:0xf bank_mask:0xf bound_ctrl:1
	s_nop 1
	v_add_f32_dpp v108, v108, v108 row_half_mirror row_mask:0xf bank_mask:0xf bound_ctrl:1
	s_nop 1
	v_add_f32_dpp v108, v108, v108 row_mirror row_mask:0xf bank_mask:0xf bound_ctrl:1
	v_mov_b32_e32 v114, v108
	s_nop 1
	v_permlane16_swap_b32 v108, v114
	s_nop 0
	v_add_f32_e32 v108, v108, v114
	v_mov_b32_e32 v114, v108
	s_nop 1
	v_permlane32_swap_b32 v108, v114
	s_nop 0
	v_add_f32_e32 v108, v108, v114
	v_mul_f32_e32 v110, 0x3a800000, v108
	v_pk_add_f32 v[8:9], v[8:9], v[110:111] op_sel_hi:[1,0] neg_lo:[0,1] neg_hi:[0,1]
	v_pk_add_f32 v[10:11], v[10:11], v[110:111] op_sel_hi:[1,0] neg_lo:[0,1] neg_hi:[0,1]
	v_pk_add_f32 v[12:13], v[12:13], v[110:111] op_sel_hi:[1,0] neg_lo:[0,1] neg_hi:[0,1]
	v_pk_add_f32 v[14:15], v[14:15], v[110:111] op_sel_hi:[1,0] neg_lo:[0,1] neg_hi:[0,1]
	v_pk_add_f32 v[20:21], v[20:21], v[110:111] op_sel_hi:[1,0] neg_lo:[0,1] neg_hi:[0,1]
	v_pk_add_f32 v[22:23], v[22:23], v[110:111] op_sel_hi:[1,0] neg_lo:[0,1] neg_hi:[0,1]
	v_pk_add_f32 v[24:25], v[24:25], v[110:111] op_sel_hi:[1,0] neg_lo:[0,1] neg_hi:[0,1]
	v_pk_add_f32 v[26:27], v[26:27], v[110:111] op_sel_hi:[1,0] neg_lo:[0,1] neg_hi:[0,1]
	v_pk_mul_f32 v[108:109], v[8:9], v[8:9]
	v_pk_fma_f32 v[108:109], v[10:11], v[10:11], v[108:109]
	v_pk_fma_f32 v[108:109], v[12:13], v[12:13], v[108:109]
	v_pk_fma_f32 v[108:109], v[14:15], v[14:15], v[108:109]
	v_pk_fma_f32 v[108:109], v[20:21], v[20:21], v[108:109]
	v_pk_fma_f32 v[108:109], v[22:23], v[22:23], v[108:109]
	v_pk_fma_f32 v[108:109], v[24:25], v[24:25], v[108:109]
	v_pk_fma_f32 v[108:109], v[26:27], v[26:27], v[108:109]
	v_add_f32_e32 v108, v108, v109
	s_nop 1
	v_add_f32_dpp v108, v108, v108 quad_perm:[1,0,3,2] row_mask:0xf bank_mask:0xf bound_ctrl:1
	s_nop 1
	v_add_f32_dpp v108, v108, v108 quad_perm:[2,3,0,1] row_mask:0xf bank_mask:0xf bound_ctrl:1
	s_nop 1
	v_add_f32_dpp v108, v108, v108 row_half_mirror row_mask:0xf bank_mask:0xf bound_ctrl:1
	s_nop 1
	v_add_f32_dpp v108, v108, v108 row_mirror row_mask:0xf bank_mask:0xf bound_ctrl:1
	v_mov_b32_e32 v114, v108
	s_nop 1
	v_permlane16_swap_b32 v108, v114
	s_nop 0
	v_add_f32_e32 v108, v108, v114
	v_mov_b32_e32 v114, v108
	s_nop 1
	v_permlane32_swap_b32 v108, v114
	s_nop 0
	v_add_f32_e32 v108, v108, v114
	v_mul_f32_e32 v112, 0x3a800000, v108
	v_add_f32_e32 v112, 0x3727c5ac, v112
	v_rsq_f32_e32 v112, v112
	s_nop 0
	v_pk_mul_f32 v[116:117], v[204:205], v[112:113] op_sel_hi:[1,0]
	v_pk_fma_f32 v[8:9], v[8:9], v[116:117], v[240:241]
	v_pk_mul_f32 v[116:117], v[206:207], v[112:113] op_sel_hi:[1,0]
	v_pk_fma_f32 v[10:11], v[10:11], v[116:117], v[242:243]
	v_pk_mul_f32 v[116:117], v[208:209], v[112:113] op_sel_hi:[1,0]
	v_pk_fma_f32 v[12:13], v[12:13], v[116:117], v[244:245]
	v_pk_mul_f32 v[116:117], v[210:211], v[112:113] op_sel_hi:[1,0]
	v_pk_fma_f32 v[14:15], v[14:15], v[116:117], v[246:247]
	v_pk_mul_f32 v[116:117], v[212:213], v[112:113] op_sel_hi:[1,0]
	v_pk_fma_f32 v[20:21], v[20:21], v[116:117], v[248:249]
	v_pk_mul_f32 v[116:117], v[214:215], v[112:113] op_sel_hi:[1,0]
	v_pk_fma_f32 v[22:23], v[22:23], v[116:117], v[250:251]
	v_pk_mul_f32 v[116:117], v[216:217], v[112:113] op_sel_hi:[1,0]
	v_pk_fma_f32 v[24:25], v[24:25], v[116:117], v[124:125]
	v_pk_mul_f32 v[116:117], v[218:219], v[112:113] op_sel_hi:[1,0]
	v_pk_fma_f32 v[26:27], v[26:27], v[116:117], v[126:127]
	v_mul_f32_e32 v118, 0xbfb8aa3b, v8
	v_mul_f32_e32 v119, 0xbfb8aa3b, v9
	v_mul_f32_e32 v120, 0xbfb8aa3b, v10
	v_mul_f32_e32 v121, 0xbfb8aa3b, v11
	v_mul_f32_e32 v122, 0xbfb8aa3b, v12
	v_mul_f32_e32 v123, 0xbfb8aa3b, v13
	v_mul_f32_e32 v108, 0xbfb8aa3b, v14
	v_mul_f32_e32 v109, 0xbfb8aa3b, v15
	v_mul_f32_e32 v110, 0xbfb8aa3b, v20
	v_mul_f32_e32 v111, 0xbfb8aa3b, v21
	v_mul_f32_e32 v112, 0xbfb8aa3b, v22
	v_mul_f32_e32 v113, 0xbfb8aa3b, v23
	v_mul_f32_e32 v114, 0xbfb8aa3b, v24
	v_mul_f32_e32 v115, 0xbfb8aa3b, v25
	v_mul_f32_e32 v116, 0xbfb8aa3b, v26
	v_mul_f32_e32 v117, 0xbfb8aa3b, v27
	v_exp_f32_e32 v118, v118
	v_exp_f32_e32 v119, v119
	v_exp_f32_e32 v120, v120
	v_exp_f32_e32 v121, v121
	v_exp_f32_e32 v122, v122
	v_exp_f32_e32 v123, v123
	v_exp_f32_e32 v108, v108
	v_exp_f32_e32 v109, v109
	v_exp_f32_e32 v110, v110
	v_exp_f32_e32 v111, v111
	v_exp_f32_e32 v112, v112
	v_exp_f32_e32 v113, v113
	v_exp_f32_e32 v114, v114
	v_exp_f32_e32 v115, v115
	v_exp_f32_e32 v116, v116
	v_exp_f32_e32 v117, v117
	v_add_f32_e32 v118, 1.0, v118
	v_add_f32_e32 v119, 1.0, v119
	v_add_f32_e32 v120, 1.0, v120
	v_add_f32_e32 v121, 1.0, v121
	v_add_f32_e32 v122, 1.0, v122
	v_add_f32_e32 v123, 1.0, v123
	v_add_f32_e32 v108, 1.0, v108
	v_add_f32_e32 v109, 1.0, v109
	v_add_f32_e32 v110, 1.0, v110
	v_add_f32_e32 v111, 1.0, v111
	v_add_f32_e32 v112, 1.0, v112
	v_add_f32_e32 v113, 1.0, v113
	v_add_f32_e32 v114, 1.0, v114
	v_add_f32_e32 v115, 1.0, v115
	v_add_f32_e32 v116, 1.0, v116
	v_add_f32_e32 v117, 1.0, v117
	v_rcp_f32_e32 v118, v118
	v_rcp_f32_e32 v119, v119
	v_rcp_f32_e32 v120, v120
	v_rcp_f32_e32 v121, v121
	v_rcp_f32_e32 v122, v122
	v_rcp_f32_e32 v123, v123
	v_rcp_f32_e32 v108, v108
	v_rcp_f32_e32 v109, v109
	v_rcp_f32_e32 v110, v110
	v_rcp_f32_e32 v111, v111
	v_rcp_f32_e32 v112, v112
	v_rcp_f32_e32 v113, v113
	v_rcp_f32_e32 v114, v114
	v_rcp_f32_e32 v115, v115
	v_rcp_f32_e32 v116, v116
	v_rcp_f32_e32 v117, v117
	v_mul_f32_e32 v8, v8, v118
	v_mul_f32_e32 v9, v9, v119
	v_mul_f32_e32 v10, v10, v120
	v_mul_f32_e32 v11, v11, v121
	v_mul_f32_e32 v12, v12, v122
	v_mul_f32_e32 v13, v13, v123
	v_mul_f32_e32 v14, v14, v108
	v_mul_f32_e32 v15, v15, v109
	v_mul_f32_e32 v20, v20, v110
	v_mul_f32_e32 v21, v21, v111
	v_mul_f32_e32 v22, v22, v112
	v_mul_f32_e32 v23, v23, v113
	v_mul_f32_e32 v24, v24, v114
	v_mul_f32_e32 v25, v25, v115
	v_mul_f32_e32 v26, v26, v116
	v_mul_f32_e32 v27, v27, v117
	v_pk_mul_f32 v[8:9], v[8:9], v[128:129]
	v_pk_mul_f32 v[10:11], v[10:11], v[130:131]
	v_pk_mul_f32 v[12:13], v[12:13], v[132:133]
	v_pk_mul_f32 v[14:15], v[14:15], v[134:135]
	v_pk_mul_f32 v[20:21], v[20:21], v[0:1]
	v_pk_mul_f32 v[22:23], v[22:23], v[2:3]
	v_pk_mul_f32 v[24:25], v[24:25], v[4:5]
	v_pk_mul_f32 v[26:27], v[26:27], v[6:7]
	v_cvt_pk_bf16_f32 v8, v8, v9
	v_cvt_pk_bf16_f32 v9, v10, v11
	v_cvt_pk_bf16_f32 v12, v12, v13
	v_cvt_pk_bf16_f32 v13, v14, v15
	v_cvt_pk_bf16_f32 v20, v20, v21
	v_cvt_pk_bf16_f32 v21, v22, v23
	v_cvt_pk_bf16_f32 v24, v24, v25
	v_cvt_pk_bf16_f32 v25, v26, v27
	global_store_dwordx2 v19, v[8:9], s[8:9] offset:0
	global_store_dwordx2 v19, v[12:13], s[8:9] offset:512
	global_store_dwordx2 v19, v[20:21], s[8:9] offset:1024
	global_store_dwordx2 v19, v[24:25], s[8:9] offset:1536
	s_add_u32 s8, s8, 0x800000
	s_addc_u32 s9, s9, 0
	v_mov_b32_e32 v108, v202
	v_mov_b32_e32 v109, v203
	v_mov_b32_e32 v110, v202
	v_mov_b32_e32 v111, v203
	v_mov_b32_e32 v112, v202
	v_mov_b32_e32 v113, v203
	v_mov_b32_e32 v114, v202
	v_mov_b32_e32 v115, v203
	v_mov_b32_e32 v116, v202
	v_mov_b32_e32 v117, v203
	v_mov_b32_e32 v118, v202
	v_mov_b32_e32 v119, v203
	v_mov_b32_e32 v120, v202
	v_mov_b32_e32 v121, v203
	v_mov_b32_e32 v122, v202
	v_mov_b32_e32 v123, v203
	s_waitcnt vmcnt(40)
	v_pk_fma_f32 v[108:109], v[140:141], v[32:33], v[108:109]
	v_pk_fma_f32 v[108:109], v[142:143], v[34:35], v[108:109]
	v_pk_fma_f32 v[110:111], v[140:141], v[34:35], v[110:111]
	s_waitcnt vmcnt(38)
	v_pk_fma_f32 v[108:109], v[144:145], v[36:37], v[108:109]
	v_pk_fma_f32 v[110:111], v[142:143], v[36:37], v[110:111]
	v_pk_fma_f32 v[112:113], v[140:141], v[36:37], v[112:113]
	v_pk_fma_f32 v[108:109], v[146:147], v[38:39], v[108:109]
	v_pk_fma_f32 v[110:111], v[144:145], v[38:39], v[110:111]
	v_pk_fma_f32 v[112:113], v[142:143], v[38:39], v[112:113]
	v_pk_fma_f32 v[114:115], v[140:141], v[38:39], v[114:115]
	s_waitcnt vmcnt(36)
	v_pk_fma_f32 v[108:109], v[148:149], v[40:41], v[108:109]
	v_pk_fma_f32 v[110:111], v[146:147], v[40:41], v[110:111]
	v_pk_fma_f32 v[112:113], v[144:145], v[40:41], v[112:113]
	v_pk_fma_f32 v[114:115], v[142:143], v[40:41], v[114:115]
	v_pk_fma_f32 v[116:117], v[140:141], v[40:41], v[116:117]
	v_pk_fma_f32 v[108:109], v[150:151], v[42:43], v[108:109]
	v_pk_fma_f32 v[110:111], v[148:149], v[42:43], v[110:111]
	v_pk_fma_f32 v[112:113], v[146:147], v[42:43], v[112:113]
	v_pk_fma_f32 v[114:115], v[144:145], v[42:43], v[114:115]
	v_pk_fma_f32 v[116:117], v[142:143], v[42:43], v[116:117]
	v_pk_fma_f32 v[118:119], v[140:141], v[42:43], v[118:119]
	s_waitcnt vmcnt(34)
	v_pk_fma_f32 v[108:109], v[152:153], v[44:45], v[108:109]
	v_pk_fma_f32 v[110:111], v[150:151], v[44:45], v[110:111]
	v_pk_fma_f32 v[112:113], v[148:149], v[44:45], v[112:113]
	v_pk_fma_f32 v[114:115], v[146:147], v[44:45], v[114:115]
	v_pk_fma_f32 v[116:117], v[144:145], v[44:45], v[116:117]
	v_pk_fma_f32 v[118:119], v[142:143], v[44:45], v[118:119]
	v_pk_fma_f32 v[120:121], v[140:141], v[44:45], v[120:121]
	v_pk_fma_f32 v[108:109], v[154:155], v[46:47], v[108:109]
	v_pk_fma_f32 v[110:111], v[152:153], v[46:47], v[110:111]
	v_pk_fma_f32 v[112:113], v[150:151], v[46:47], v[112:113]
	v_pk_fma_f32 v[114:115], v[148:149], v[46:47], v[114:115]
	v_pk_fma_f32 v[116:117], v[146:147], v[46:47], v[116:117]
	v_pk_fma_f32 v[118:119], v[144:145], v[46:47], v[118:119]
	v_pk_fma_f32 v[120:121], v[142:143], v[46:47], v[120:121]
	v_pk_fma_f32 v[122:123], v[140:141], v[46:47], v[122:123]
	s_waitcnt vmcnt(32)
	v_pk_fma_f32 v[108:109], v[156:157], v[48:49], v[108:109]
	v_pk_fma_f32 v[110:111], v[154:155], v[48:49], v[110:111]
	v_pk_fma_f32 v[112:113], v[152:153], v[48:49], v[112:113]
	v_pk_fma_f32 v[114:115], v[150:151], v[48:49], v[114:115]
	v_pk_fma_f32 v[116:117], v[148:149], v[48:49], v[116:117]
	v_pk_fma_f32 v[118:119], v[146:147], v[48:49], v[118:119]
	v_pk_fma_f32 v[120:121], v[144:145], v[48:49], v[120:121]
	v_pk_fma_f32 v[122:123], v[142:143], v[48:49], v[122:123]
	v_pk_fma_f32 v[108:109], v[158:159], v[50:51], v[108:109]
	v_pk_fma_f32 v[110:111], v[156:157], v[50:51], v[110:111]
	v_pk_fma_f32 v[112:113], v[154:155], v[50:51], v[112:113]
	v_pk_fma_f32 v[114:115], v[152:153], v[50:51], v[114:115]
	v_pk_fma_f32 v[116:117], v[150:151], v[50:51], v[116:117]
	v_pk_fma_f32 v[118:119], v[148:149], v[50:51], v[118:119]
	v_pk_fma_f32 v[120:121], v[146:147], v[50:51], v[120:121]
	v_pk_fma_f32 v[122:123], v[144:145], v[50:51], v[122:123]
	s_waitcnt vmcnt(30)
	v_pk_fma_f32 v[108:109], v[160:161], v[52:53], v[108:109]
	v_pk_fma_f32 v[110:111], v[158:159], v[52:53], v[110:111]
	v_pk_fma_f32 v[112:113], v[156:157], v[52:53], v[112:113]
	v_pk_fma_f32 v[114:115], v[154:155], v[52:53], v[114:115]
	v_pk_fma_f32 v[116:117], v[152:153], v[52:53], v[116:117]
	v_pk_fma_f32 v[118:119], v[150:151], v[52:53], v[118:119]
	v_pk_fma_f32 v[120:121], v[148:149], v[52:53], v[120:121]
	v_pk_fma_f32 v[122:123], v[146:147], v[52:53], v[122:123]
	v_pk_fma_f32 v[108:109], v[162:163], v[54:55], v[108:109]
	v_pk_fma_f32 v[110:111], v[160:161], v[54:55], v[110:111]
	v_pk_fma_f32 v[112:113], v[158:159], v[54:55], v[112:113]
	v_pk_fma_f32 v[114:115], v[156:157], v[54:55], v[114:115]
	v_pk_fma_f32 v[116:117], v[154:155], v[54:55], v[116:117]
	v_pk_fma_f32 v[118:119], v[152:153], v[54:55], v[118:119]
	v_pk_fma_f32 v[120:121], v[150:151], v[54:55], v[120:121]
	v_pk_fma_f32 v[122:123], v[148:149], v[54:55], v[122:123]
	s_waitcnt vmcnt(28)
	v_pk_fma_f32 v[108:109], v[164:165], v[56:57], v[108:109]
	v_pk_fma_f32 v[110:111], v[162:163], v[56:57], v[110:111]
	v_pk_fma_f32 v[112:113], v[160:161], v[56:57], v[112:113]
	v_pk_fma_f32 v[114:115], v[158:159], v[56:57], v[114:115]
	v_pk_fma_f32 v[116:117], v[156:157], v[56:57], v[116:117]
	v_pk_fma_f32 v[118:119], v[154:155], v[56:57], v[118:119]
	v_pk_fma_f32 v[120:121], v[152:153], v[56:57], v[120:121]
	v_pk_fma_f32 v[122:123], v[150:151], v[56:57], v[122:123]
	v_pk_fma_f32 v[108:109], v[166:167], v[58:59], v[108:109]
	v_pk_fma_f32 v[110:111], v[164:165], v[58:59], v[110:111]
	v_pk_fma_f32 v[112:113], v[162:163], v[58:59], v[112:113]
	v_pk_fma_f32 v[114:115], v[160:161], v[58:59], v[114:115]
	v_pk_fma_f32 v[116:117], v[158:159], v[58:59], v[116:117]
	v_pk_fma_f32 v[118:119], v[156:157], v[58:59], v[118:119]
	v_pk_fma_f32 v[120:121], v[154:155], v[58:59], v[120:121]
	v_pk_fma_f32 v[122:123], v[152:153], v[58:59], v[122:123]
	s_waitcnt vmcnt(26)
	v_pk_fma_f32 v[108:109], v[168:169], v[60:61], v[108:109]
	v_pk_fma_f32 v[110:111], v[166:167], v[60:61], v[110:111]
	v_pk_fma_f32 v[112:113], v[164:165], v[60:61], v[112:113]
	v_pk_fma_f32 v[114:115], v[162:163], v[60:61], v[114:115]
	v_pk_fma_f32 v[116:117], v[160:161], v[60:61], v[116:117]
	v_pk_fma_f32 v[118:119], v[158:159], v[60:61], v[118:119]
	v_pk_fma_f32 v[120:121], v[156:157], v[60:61], v[120:121]
	v_pk_fma_f32 v[122:123], v[154:155], v[60:61], v[122:123]
	v_pk_fma_f32 v[108:109], v[170:171], v[62:63], v[108:109]
	v_pk_fma_f32 v[110:111], v[168:169], v[62:63], v[110:111]
	v_pk_fma_f32 v[112:113], v[166:167], v[62:63], v[112:113]
	v_pk_fma_f32 v[114:115], v[164:165], v[62:63], v[114:115]
	v_pk_fma_f32 v[116:117], v[162:163], v[62:63], v[116:117]
	v_pk_fma_f32 v[118:119], v[160:161], v[62:63], v[118:119]
	v_pk_fma_f32 v[120:121], v[158:159], v[62:63], v[120:121]
	v_pk_fma_f32 v[122:123], v[156:157], v[62:63], v[122:123]
	s_waitcnt vmcnt(24)
	v_pk_fma_f32 v[108:109], v[172:173], v[64:65], v[108:109]
	v_pk_fma_f32 v[110:111], v[170:171], v[64:65], v[110:111]
	v_pk_fma_f32 v[112:113], v[168:169], v[64:65], v[112:113]
	v_pk_fma_f32 v[114:115], v[166:167], v[64:65], v[114:115]
	v_pk_fma_f32 v[116:117], v[164:165], v[64:65], v[116:117]
	v_pk_fma_f32 v[118:119], v[162:163], v[64:65], v[118:119]
	v_pk_fma_f32 v[120:121], v[160:161], v[64:65], v[120:121]
	v_pk_fma_f32 v[122:123], v[158:159], v[64:65], v[122:123]
	v_pk_fma_f32 v[108:109], v[174:175], v[66:67], v[108:109]
	v_pk_fma_f32 v[110:111], v[172:173], v[66:67], v[110:111]
	v_pk_fma_f32 v[112:113], v[170:171], v[66:67], v[112:113]
	v_pk_fma_f32 v[114:115], v[168:169], v[66:67], v[114:115]
	v_pk_fma_f32 v[116:117], v[166:167], v[66:67], v[116:117]
	v_pk_fma_f32 v[118:119], v[164:165], v[66:67], v[118:119]
	v_pk_fma_f32 v[120:121], v[162:163], v[66:67], v[120:121]
	v_pk_fma_f32 v[122:123], v[160:161], v[66:67], v[122:123]
	s_waitcnt vmcnt(22)
	v_pk_fma_f32 v[108:109], v[176:177], v[68:69], v[108:109]
	v_pk_fma_f32 v[110:111], v[174:175], v[68:69], v[110:111]
	v_pk_fma_f32 v[112:113], v[172:173], v[68:69], v[112:113]
	v_pk_fma_f32 v[114:115], v[170:171], v[68:69], v[114:115]
	v_pk_fma_f32 v[116:117], v[168:169], v[68:69], v[116:117]
	v_pk_fma_f32 v[118:119], v[166:167], v[68:69], v[118:119]
	v_pk_fma_f32 v[120:121], v[164:165], v[68:69], v[120:121]
	v_pk_fma_f32 v[122:123], v[162:163], v[68:69], v[122:123]
	v_pk_fma_f32 v[108:109], v[178:179], v[70:71], v[108:109]
	v_pk_fma_f32 v[110:111], v[176:177], v[70:71], v[110:111]
	v_pk_fma_f32 v[112:113], v[174:175], v[70:71], v[112:113]
	v_pk_fma_f32 v[114:115], v[172:173], v[70:71], v[114:115]
	v_pk_fma_f32 v[116:117], v[170:171], v[70:71], v[116:117]
	v_pk_fma_f32 v[118:119], v[168:169], v[70:71], v[118:119]
	v_pk_fma_f32 v[120:121], v[166:167], v[70:71], v[120:121]
	v_pk_fma_f32 v[122:123], v[164:165], v[70:71], v[122:123]
	s_waitcnt vmcnt(20)
	v_pk_fma_f32 v[108:109], v[180:181], v[72:73], v[108:109]
	v_pk_fma_f32 v[110:111], v[178:179], v[72:73], v[110:111]
	v_pk_fma_f32 v[112:113], v[176:177], v[72:73], v[112:113]
	v_pk_fma_f32 v[114:115], v[174:175], v[72:73], v[114:115]
	v_pk_fma_f32 v[116:117], v[172:173], v[72:73], v[116:117]
	v_pk_fma_f32 v[118:119], v[170:171], v[72:73], v[118:119]
	v_pk_fma_f32 v[120:121], v[168:169], v[72:73], v[120:121]
	v_pk_fma_f32 v[122:123], v[166:167], v[72:73], v[122:123]
	v_pk_fma_f32 v[108:109], v[182:183], v[74:75], v[108:109]
	v_pk_fma_f32 v[110:111], v[180:181], v[74:75], v[110:111]
	v_pk_fma_f32 v[112:113], v[178:179], v[74:75], v[112:113]
	v_pk_fma_f32 v[114:115], v[176:177], v[74:75], v[114:115]
	v_pk_fma_f32 v[116:117], v[174:175], v[74:75], v[116:117]
	v_pk_fma_f32 v[118:119], v[172:173], v[74:75], v[118:119]
	v_pk_fma_f32 v[120:121], v[170:171], v[74:75], v[120:121]
	v_pk_fma_f32 v[122:123], v[168:169], v[74:75], v[122:123]
	s_waitcnt vmcnt(18)
	v_pk_fma_f32 v[108:109], v[184:185], v[76:77], v[108:109]
	v_pk_fma_f32 v[110:111], v[182:183], v[76:77], v[110:111]
	v_pk_fma_f32 v[112:113], v[180:181], v[76:77], v[112:113]
	v_pk_fma_f32 v[114:115], v[178:179], v[76:77], v[114:115]
	v_pk_fma_f32 v[116:117], v[176:177], v[76:77], v[116:117]
	v_pk_fma_f32 v[118:119], v[174:175], v[76:77], v[118:119]
	v_pk_fma_f32 v[120:121], v[172:173], v[76:77], v[120:121]
	v_pk_fma_f32 v[122:123], v[170:171], v[76:77], v[122:123]
	v_pk_fma_f32 v[108:109], v[186:187], v[78:79], v[108:109]
	v_pk_fma_f32 v[110:111], v[184:185], v[78:79], v[110:111]
	v_pk_fma_f32 v[112:113], v[182:183], v[78:79], v[112:113]
	v_pk_fma_f32 v[114:115], v[180:181], v[78:79], v[114:115]
	v_pk_fma_f32 v[116:117], v[178:179], v[78:79], v[116:117]
	v_pk_fma_f32 v[118:119], v[176:177], v[78:79], v[118:119]
	v_pk_fma_f32 v[120:121], v[174:175], v[78:79], v[120:121]
	v_pk_fma_f32 v[122:123], v[172:173], v[78:79], v[122:123]
	s_waitcnt vmcnt(16)
	v_pk_fma_f32 v[108:109], v[188:189], v[80:81], v[108:109]
	v_pk_fma_f32 v[110:111], v[186:187], v[80:81], v[110:111]
	v_pk_fma_f32 v[112:113], v[184:185], v[80:81], v[112:113]
	v_pk_fma_f32 v[114:115], v[182:183], v[80:81], v[114:115]
	v_pk_fma_f32 v[116:117], v[180:181], v[80:81], v[116:117]
	v_pk_fma_f32 v[118:119], v[178:179], v[80:81], v[118:119]
	v_pk_fma_f32 v[120:121], v[176:177], v[80:81], v[120:121]
	v_pk_fma_f32 v[122:123], v[174:175], v[80:81], v[122:123]
	v_pk_fma_f32 v[108:109], v[190:191], v[82:83], v[108:109]
	v_pk_fma_f32 v[110:111], v[188:189], v[82:83], v[110:111]
	v_pk_fma_f32 v[112:113], v[186:187], v[82:83], v[112:113]
	v_pk_fma_f32 v[114:115], v[184:185], v[82:83], v[114:115]
	v_pk_fma_f32 v[116:117], v[182:183], v[82:83], v[116:117]
	v_pk_fma_f32 v[118:119], v[180:181], v[82:83], v[118:119]
	v_pk_fma_f32 v[120:121], v[178:179], v[82:83], v[120:121]
	v_pk_fma_f32 v[122:123], v[176:177], v[82:83], v[122:123]
	s_waitcnt vmcnt(14)
	v_pk_fma_f32 v[108:109], v[192:193], v[84:85], v[108:109]
	v_pk_fma_f32 v[110:111], v[190:191], v[84:85], v[110:111]
	v_pk_fma_f32 v[112:113], v[188:189], v[84:85], v[112:113]
	v_pk_fma_f32 v[114:115], v[186:187], v[84:85], v[114:115]
	v_pk_fma_f32 v[116:117], v[184:185], v[84:85], v[116:117]
	v_pk_fma_f32 v[118:119], v[182:183], v[84:85], v[118:119]
	v_pk_fma_f32 v[120:121], v[180:181], v[84:85], v[120:121]
	v_pk_fma_f32 v[122:123], v[178:179], v[84:85], v[122:123]
	v_pk_fma_f32 v[108:109], v[194:195], v[86:87], v[108:109]
	v_pk_fma_f32 v[110:111], v[192:193], v[86:87], v[110:111]
	v_pk_fma_f32 v[112:113], v[190:191], v[86:87], v[112:113]
	v_pk_fma_f32 v[114:115], v[188:189], v[86:87], v[114:115]
	v_pk_fma_f32 v[116:117], v[186:187], v[86:87], v[116:117]
	v_pk_fma_f32 v[118:119], v[184:185], v[86:87], v[118:119]
	v_pk_fma_f32 v[120:121], v[182:183], v[86:87], v[120:121]
	v_pk_fma_f32 v[122:123], v[180:181], v[86:87], v[122:123]
	s_waitcnt vmcnt(12)
	v_pk_fma_f32 v[108:109], v[196:197], v[88:89], v[108:109]
	v_pk_fma_f32 v[110:111], v[194:195], v[88:89], v[110:111]
	v_pk_fma_f32 v[112:113], v[192:193], v[88:89], v[112:113]
	v_pk_fma_f32 v[114:115], v[190:191], v[88:89], v[114:115]
	v_pk_fma_f32 v[116:117], v[188:189], v[88:89], v[116:117]
	v_pk_fma_f32 v[118:119], v[186:187], v[88:89], v[118:119]
	v_pk_fma_f32 v[120:121], v[184:185], v[88:89], v[120:121]
	v_pk_fma_f32 v[122:123], v[182:183], v[88:89], v[122:123]
	v_pk_fma_f32 v[108:109], v[198:199], v[90:91], v[108:109]
	v_pk_fma_f32 v[110:111], v[196:197], v[90:91], v[110:111]
	v_pk_fma_f32 v[112:113], v[194:195], v[90:91], v[112:113]
	v_pk_fma_f32 v[114:115], v[192:193], v[90:91], v[114:115]
	v_pk_fma_f32 v[116:117], v[190:191], v[90:91], v[116:117]
	v_pk_fma_f32 v[118:119], v[188:189], v[90:91], v[118:119]
	v_pk_fma_f32 v[120:121], v[186:187], v[90:91], v[120:121]
	v_pk_fma_f32 v[122:123], v[184:185], v[90:91], v[122:123]
	s_waitcnt vmcnt(10)
	v_pk_fma_f32 v[108:109], v[200:201], v[92:93], v[108:109]
	v_pk_fma_f32 v[110:111], v[198:199], v[92:93], v[110:111]
	v_pk_fma_f32 v[112:113], v[196:197], v[92:93], v[112:113]
	v_pk_fma_f32 v[114:115], v[194:195], v[92:93], v[114:115]
	v_pk_fma_f32 v[116:117], v[192:193], v[92:93], v[116:117]
	v_pk_fma_f32 v[118:119], v[190:191], v[92:93], v[118:119]
	v_pk_fma_f32 v[120:121], v[188:189], v[92:93], v[120:121]
	v_pk_fma_f32 v[122:123], v[186:187], v[92:93], v[122:123]
	v_pk_fma_f32 v[110:111], v[200:201], v[94:95], v[110:111]
	v_pk_fma_f32 v[112:113], v[198:199], v[94:95], v[112:113]
	v_pk_fma_f32 v[114:115], v[196:197], v[94:95], v[114:115]
	v_pk_fma_f32 v[116:117], v[194:195], v[94:95], v[116:117]
	v_pk_fma_f32 v[118:119], v[192:193], v[94:95], v[118:119]
	v_pk_fma_f32 v[120:121], v[190:191], v[94:95], v[120:121]
	v_pk_fma_f32 v[122:123], v[188:189], v[94:95], v[122:123]
	s_waitcnt vmcnt(8)
	v_pk_fma_f32 v[112:113], v[200:201], v[96:97], v[112:113]
	v_pk_fma_f32 v[114:115], v[198:199], v[96:97], v[114:115]
	v_pk_fma_f32 v[116:117], v[196:197], v[96:97], v[116:117]
	v_pk_fma_f32 v[118:119], v[194:195], v[96:97], v[118:119]
	v_pk_fma_f32 v[120:121], v[192:193], v[96:97], v[120:121]
	v_pk_fma_f32 v[122:123], v[190:191], v[96:97], v[122:123]
	v_pk_fma_f32 v[114:115], v[200:201], v[98:99], v[114:115]
	v_pk_fma_f32 v[116:117], v[198:199], v[98:99], v[116:117]
	v_pk_fma_f32 v[118:119], v[196:197], v[98:99], v[118:119]
	v_pk_fma_f32 v[120:121], v[194:195], v[98:99], v[120:121]
	v_pk_fma_f32 v[122:123], v[192:193], v[98:99], v[122:123]
	s_waitcnt vmcnt(6)
	v_pk_fma_f32 v[116:117], v[200:201], v[100:101], v[116:117]
	v_pk_fma_f32 v[118:119], v[198:199], v[100:101], v[118:119]
	v_pk_fma_f32 v[120:121], v[196:197], v[100:101], v[120:121]
	v_pk_fma_f32 v[122:123], v[194:195], v[100:101], v[122:123]
	v_pk_fma_f32 v[118:119], v[200:201], v[102:103], v[118:119]
	v_pk_fma_f32 v[120:121], v[198:199], v[102:103], v[120:121]
	v_pk_fma_f32 v[122:123], v[196:197], v[102:103], v[122:123]
	s_waitcnt vmcnt(4)
	v_pk_fma_f32 v[120:121], v[200:201], v[104:105], v[120:121]
	v_pk_fma_f32 v[122:123], v[198:199], v[104:105], v[122:123]
	v_pk_fma_f32 v[122:123], v[200:201], v[106:107], v[122:123]
	ds_write_b64 v16, v[108:109] offset:0
	ds_write_b64 v16, v[110:111] offset:4096
	ds_write_b64 v16, v[112:113] offset:8192
	ds_write_b64 v16, v[114:115] offset:12288
	ds_write_b64 v16, v[116:117] offset:16384
	ds_write_b64 v16, v[118:119] offset:20480
	ds_write_b64 v16, v[120:121] offset:24576
	ds_write_b64 v16, v[122:123] offset:28672
	s_waitcnt lgkmcnt(0)
	s_barrier
	ds_read_b128 v[8:11], v17 offset:0
	ds_read_b128 v[12:15], v17 offset:1024
	ds_read_b128 v[20:23], v17 offset:2048
	ds_read_b128 v[24:27], v17 offset:3072
	s_waitcnt lgkmcnt(0)
	s_barrier
	v_pk_add_f32 v[108:109], v[8:9], v[10:11]
	v_pk_add_f32 v[108:109], v[108:109], v[12:13]
	v_pk_add_f32 v[108:109], v[108:109], v[14:15]
	v_pk_add_f32 v[108:109], v[108:109], v[20:21]
	v_pk_add_f32 v[108:109], v[108:109], v[22:23]
	v_pk_add_f32 v[108:109], v[108:109], v[24:25]
	v_pk_add_f32 v[108:109], v[108:109], v[26:27]
	v_add_f32_e32 v108, v108, v109
	s_nop 1
	v_add_f32_dpp v108, v108, v108 quad_perm:[1,0,3,2] row_mask:0xf bank_mask:0xf bound_ctrl:1
	s_nop 1
	v_add_f32_dpp v108, v108, v108 quad_perm:[2,3,0,1] row_mask:0xf bank_mask:0xf bound_ctrl:1
	s_nop 1
	v_add_f32_dpp v108, v108, v108 row_half_mirror row_mask:0xf bank_mask:0xf bound_ctrl:1
	s_nop 1
	v_add_f32_dpp v108, v108, v108 row_mirror row_mask:0xf bank_mask:0xf bound_ctrl:1
	v_mov_b32_e32 v114, v108
	s_nop 1
	v_permlane16_swap_b32 v108, v114
	s_nop 0
	v_add_f32_e32 v108, v108, v114
	v_mov_b32_e32 v114, v108
	s_nop 1
	v_permlane32_swap_b32 v108, v114
	s_nop 0
	v_add_f32_e32 v108, v108, v114
	v_mul_f32_e32 v110, 0x3a800000, v108
	v_pk_add_f32 v[8:9], v[8:9], v[110:111] op_sel_hi:[1,0] neg_lo:[0,1] neg_hi:[0,1]
	v_pk_add_f32 v[10:11], v[10:11], v[110:111] op_sel_hi:[1,0] neg_lo:[0,1] neg_hi:[0,1]
	v_pk_add_f32 v[12:13], v[12:13], v[110:111] op_sel_hi:[1,0] neg_lo:[0,1] neg_hi:[0,1]
	v_pk_add_f32 v[14:15], v[14:15], v[110:111] op_sel_hi:[1,0] neg_lo:[0,1] neg_hi:[0,1]
	v_pk_add_f32 v[20:21], v[20:21], v[110:111] op_sel_hi:[1,0] neg_lo:[0,1] neg_hi:[0,1]
	v_pk_add_f32 v[22:23], v[22:23], v[110:111] op_sel_hi:[1,0] neg_lo:[0,1] neg_hi:[0,1]
	v_pk_add_f32 v[24:25], v[24:25], v[110:111] op_sel_hi:[1,0] neg_lo:[0,1] neg_hi:[0,1]
	v_pk_add_f32 v[26:27], v[26:27], v[110:111] op_sel_hi:[1,0] neg_lo:[0,1] neg_hi:[0,1]
	v_pk_mul_f32 v[108:109], v[8:9], v[8:9]
	v_pk_fma_f32 v[108:109], v[10:11], v[10:11], v[108:109]
	v_pk_fma_f32 v[108:109], v[12:13], v[12:13], v[108:109]
	v_pk_fma_f32 v[108:109], v[14:15], v[14:15], v[108:109]
	v_pk_fma_f32 v[108:109], v[20:21], v[20:21], v[108:109]
	v_pk_fma_f32 v[108:109], v[22:23], v[22:23], v[108:109]
	v_pk_fma_f32 v[108:109], v[24:25], v[24:25], v[108:109]
	v_pk_fma_f32 v[108:109], v[26:27], v[26:27], v[108:109]
	v_add_f32_e32 v108, v108, v109
	s_nop 1
	v_add_f32_dpp v108, v108, v108 quad_perm:[1,0,3,2] row_mask:0xf bank_mask:0xf bound_ctrl:1
	s_nop 1
	v_add_f32_dpp v108, v108, v108 quad_perm:[2,3,0,1] row_mask:0xf bank_mask:0xf bound_ctrl:1
	s_nop 1
	v_add_f32_dpp v108, v108, v108 row_half_mirror row_mask:0xf bank_mask:0xf bound_ctrl:1
	s_nop 1
	v_add_f32_dpp v108, v108, v108 row_mirror row_mask:0xf bank_mask:0xf bound_ctrl:1
	v_mov_b32_e32 v114, v108
	s_nop 1
	v_permlane16_swap_b32 v108, v114
	s_nop 0
	v_add_f32_e32 v108, v108, v114
	v_mov_b32_e32 v114, v108
	s_nop 1
	v_permlane32_swap_b32 v108, v114
	s_nop 0
	v_add_f32_e32 v108, v108, v114
	v_mul_f32_e32 v112, 0x3a800000, v108
	v_add_f32_e32 v112, 0x3727c5ac, v112
	v_rsq_f32_e32 v112, v112
	s_nop 0
	v_pk_mul_f32 v[116:117], v[204:205], v[112:113] op_sel_hi:[1,0]
	v_pk_fma_f32 v[8:9], v[8:9], v[116:117], v[240:241]
	v_pk_mul_f32 v[116:117], v[206:207], v[112:113] op_sel_hi:[1,0]
	v_pk_fma_f32 v[10:11], v[10:11], v[116:117], v[242:243]
	v_pk_mul_f32 v[116:117], v[208:209], v[112:113] op_sel_hi:[1,0]
	v_pk_fma_f32 v[12:13], v[12:13], v[116:117], v[244:245]
	v_pk_mul_f32 v[116:117], v[210:211], v[112:113] op_sel_hi:[1,0]
	v_pk_fma_f32 v[14:15], v[14:15], v[116:117], v[246:247]
	v_pk_mul_f32 v[116:117], v[212:213], v[112:113] op_sel_hi:[1,0]
	v_pk_fma_f32 v[20:21], v[20:21], v[116:117], v[248:249]
	v_pk_mul_f32 v[116:117], v[214:215], v[112:113] op_sel_hi:[1,0]
	v_pk_fma_f32 v[22:23], v[22:23], v[116:117], v[250:251]
	v_pk_mul_f32 v[116:117], v[216:217], v[112:113] op_sel_hi:[1,0]
	v_pk_fma_f32 v[24:25], v[24:25], v[116:117], v[124:125]
	v_pk_mul_f32 v[116:117], v[218:219], v[112:113] op_sel_hi:[1,0]
	v_pk_fma_f32 v[26:27], v[26:27], v[116:117], v[126:127]
	v_mul_f32_e32 v118, 0xbfb8aa3b, v8
	v_mul_f32_e32 v119, 0xbfb8aa3b, v9
	v_mul_f32_e32 v120, 0xbfb8aa3b, v10
	v_mul_f32_e32 v121, 0xbfb8aa3b, v11
	v_mul_f32_e32 v122, 0xbfb8aa3b, v12
	v_mul_f32_e32 v123, 0xbfb8aa3b, v13
	v_mul_f32_e32 v108, 0xbfb8aa3b, v14
	v_mul_f32_e32 v109, 0xbfb8aa3b, v15
	v_mul_f32_e32 v110, 0xbfb8aa3b, v20
	v_mul_f32_e32 v111, 0xbfb8aa3b, v21
	v_mul_f32_e32 v112, 0xbfb8aa3b, v22
	v_mul_f32_e32 v113, 0xbfb8aa3b, v23
	v_mul_f32_e32 v114, 0xbfb8aa3b, v24
	v_mul_f32_e32 v115, 0xbfb8aa3b, v25
	v_mul_f32_e32 v116, 0xbfb8aa3b, v26
	v_mul_f32_e32 v117, 0xbfb8aa3b, v27
	v_exp_f32_e32 v118, v118
	v_exp_f32_e32 v119, v119
	v_exp_f32_e32 v120, v120
	v_exp_f32_e32 v121, v121
	v_exp_f32_e32 v122, v122
	v_exp_f32_e32 v123, v123
	v_exp_f32_e32 v108, v108
	v_exp_f32_e32 v109, v109
	v_exp_f32_e32 v110, v110
	v_exp_f32_e32 v111, v111
	v_exp_f32_e32 v112, v112
	v_exp_f32_e32 v113, v113
	v_exp_f32_e32 v114, v114
	v_exp_f32_e32 v115, v115
	v_exp_f32_e32 v116, v116
	v_exp_f32_e32 v117, v117
	v_add_f32_e32 v118, 1.0, v118
	v_add_f32_e32 v119, 1.0, v119
	v_add_f32_e32 v120, 1.0, v120
	v_add_f32_e32 v121, 1.0, v121
	v_add_f32_e32 v122, 1.0, v122
	v_add_f32_e32 v123, 1.0, v123
	v_add_f32_e32 v108, 1.0, v108
	v_add_f32_e32 v109, 1.0, v109
	v_add_f32_e32 v110, 1.0, v110
	v_add_f32_e32 v111, 1.0, v111
	v_add_f32_e32 v112, 1.0, v112
	v_add_f32_e32 v113, 1.0, v113
	v_add_f32_e32 v114, 1.0, v114
	v_add_f32_e32 v115, 1.0, v115
	v_add_f32_e32 v116, 1.0, v116
	v_add_f32_e32 v117, 1.0, v117
	v_rcp_f32_e32 v118, v118
	v_rcp_f32_e32 v119, v119
	v_rcp_f32_e32 v120, v120
	v_rcp_f32_e32 v121, v121
	v_rcp_f32_e32 v122, v122
	v_rcp_f32_e32 v123, v123
	v_rcp_f32_e32 v108, v108
	v_rcp_f32_e32 v109, v109
	v_rcp_f32_e32 v110, v110
	v_rcp_f32_e32 v111, v111
	v_rcp_f32_e32 v112, v112
	v_rcp_f32_e32 v113, v113
	v_rcp_f32_e32 v114, v114
	v_rcp_f32_e32 v115, v115
	v_rcp_f32_e32 v116, v116
	v_rcp_f32_e32 v117, v117
	v_mul_f32_e32 v8, v8, v118
	v_mul_f32_e32 v9, v9, v119
	v_mul_f32_e32 v10, v10, v120
	v_mul_f32_e32 v11, v11, v121
	v_mul_f32_e32 v12, v12, v122
	v_mul_f32_e32 v13, v13, v123
	v_mul_f32_e32 v14, v14, v108
	v_mul_f32_e32 v15, v15, v109
	v_mul_f32_e32 v20, v20, v110
	v_mul_f32_e32 v21, v21, v111
	v_mul_f32_e32 v22, v22, v112
	v_mul_f32_e32 v23, v23, v113
	v_mul_f32_e32 v24, v24, v114
	v_mul_f32_e32 v25, v25, v115
	v_mul_f32_e32 v26, v26, v116
	v_mul_f32_e32 v27, v27, v117
	v_pk_mul_f32 v[8:9], v[8:9], v[128:129]
	v_pk_mul_f32 v[10:11], v[10:11], v[130:131]
	v_pk_mul_f32 v[12:13], v[12:13], v[132:133]
	v_pk_mul_f32 v[14:15], v[14:15], v[134:135]
	v_pk_mul_f32 v[20:21], v[20:21], v[0:1]
	v_pk_mul_f32 v[22:23], v[22:23], v[2:3]
	v_pk_mul_f32 v[24:25], v[24:25], v[4:5]
	v_pk_mul_f32 v[26:27], v[26:27], v[6:7]
	v_cvt_pk_bf16_f32 v8, v8, v9
	v_cvt_pk_bf16_f32 v9, v10, v11
	v_cvt_pk_bf16_f32 v12, v12, v13
	v_cvt_pk_bf16_f32 v13, v14, v15
	v_cvt_pk_bf16_f32 v20, v20, v21
	v_cvt_pk_bf16_f32 v21, v22, v23
	v_cvt_pk_bf16_f32 v24, v24, v25
	v_cvt_pk_bf16_f32 v25, v26, v27
	global_store_dwordx2 v19, v[8:9], s[8:9] offset:0
	global_store_dwordx2 v19, v[12:13], s[8:9] offset:512
	global_store_dwordx2 v19, v[20:21], s[8:9] offset:1024
	global_store_dwordx2 v19, v[24:25], s[8:9] offset:1536
	s_add_u32 s8, s8, 0x800000
	s_addc_u32 s9, s9, 0
	s_cmp_lt_u32 s2, 0x80
	s_cbranch_scc0 .Lcv_nosample
	s_mul_i32 s3, s2, 0x1e000
	s_add_u32 s6, s46, s3
	s_addc_u32 s7, s47, 0
	global_load_dwordx2 v[32:33], v16, s[6:7]
	s_add_u32 s6, s6, 0x1000
	s_addc_u32 s7, s7, 0
	global_load_dwordx2 v[34:35], v16, s[6:7]
	s_add_u32 s6, s6, 0x1000
	s_addc_u32 s7, s7, 0
	global_load_dwordx2 v[36:37], v16, s[6:7]
	s_add_u32 s6, s6, 0x1000
	s_addc_u32 s7, s7, 0
	global_load_dwordx2 v[38:39], v16, s[6:7]
	s_add_u32 s6, s6, 0x1000
	s_addc_u32 s7, s7, 0
	global_load_dwordx2 v[40:41], v16, s[6:7]
	s_add_u32 s6, s6, 0x1000
	s_addc_u32 s7, s7, 0
	global_load_dwordx2 v[42:43], v16, s[6:7]
	s_add_u32 s6, s6, 0x1000
	s_addc_u32 s7, s7, 0
	global_load_dwordx2 v[44:45], v16, s[6:7]
	s_add_u32 s6, s6, 0x1000
	s_addc_u32 s7, s7, 0
	global_load_dwordx2 v[46:47], v16, s[6:7]
	s_add_u32 s6, s6, 0x1000
	s_addc_u32 s7, s7, 0
	global_load_dwordx2 v[48:49], v16, s[6:7]
	s_add_u32 s6, s6, 0x1000
	s_addc_u32 s7, s7, 0
	global_load_dwordx2 v[50:51], v16, s[6:7]
	s_add_u32 s6, s6, 0x1000
	s_addc_u32 s7, s7, 0
	global_load_dwordx2 v[52:53], v16, s[6:7]
	s_add_u32 s6, s6, 0x1000
	s_addc_u32 s7, s7, 0
	global_load_dwordx2 v[54:55], v16, s[6:7]
	s_add_u32 s6, s6, 0x1000
	s_addc_u32 s7, s7, 0
	global_load_dwordx2 v[56:57], v16, s[6:7]
	s_add_u32 s6, s6, 0x1000
	s_addc_u32 s7, s7, 0
	global_load_dwordx2 v[58:59], v16, s[6:7]
	s_add_u32 s6, s6, 0x1000
	s_addc_u32 s7, s7, 0
	global_load_dwordx2 v[60:61], v16, s[6:7]
	s_add_u32 s6, s6, 0x1000
	s_addc_u32 s7, s7, 0
	global_load_dwordx2 v[62:63], v16, s[6:7]
	s_add_u32 s6, s6, 0x1000
	s_addc_u32 s7, s7, 0
	global_load_dwordx2 v[64:65], v16, s[6:7]
	s_add_u32 s6, s6, 0x1000
	s_addc_u32 s7, s7, 0
	global_load_dwordx2 v[66:67], v16, s[6:7]
	s_add_u32 s6, s6, 0x1000
	s_addc_u32 s7, s7, 0
	global_load_dwordx2 v[68:69], v16, s[6:7]
	s_add_u32 s6, s6, 0x1000
	s_addc_u32 s7, s7, 0
	global_load_dwordx2 v[70:71], v16, s[6:7]
	s_add_u32 s6, s6, 0x1000
	s_addc_u32 s7, s7, 0
	global_load_dwordx2 v[72:73], v16, s[6:7]
	s_add_u32 s6, s6, 0x1000
	s_addc_u32 s7, s7, 0
	global_load_dwordx2 v[74:75], v16, s[6:7]
	s_add_u32 s6, s6, 0x1000
	s_addc_u32 s7, s7, 0
	global_load_dwordx2 v[76:77], v16, s[6:7]
	s_add_u32 s6, s6, 0x1000
	s_addc_u32 s7, s7, 0
	global_load_dwordx2 v[78:79], v16, s[6:7]
	s_add_u32 s6, s6, 0x1000
	s_addc_u32 s7, s7, 0
	global_load_dwordx2 v[80:81], v16, s[6:7]
	s_add_u32 s6, s6, 0x1000
	s_addc_u32 s7, s7, 0
	global_load_dwordx2 v[82:83], v16, s[6:7]
	s_add_u32 s6, s6, 0x1000
	s_addc_u32 s7, s7, 0
	global_load_dwordx2 v[84:85], v16, s[6:7]
	s_add_u32 s6, s6, 0x1000
	s_addc_u32 s7, s7, 0
	global_load_dwordx2 v[86:87], v16, s[6:7]
	s_add_u32 s6, s6, 0x1000
	s_addc_u32 s7, s7, 0
	global_load_dwordx2 v[88:89], v16, s[6:7]
	s_add_u32 s6, s6, 0x1000
	s_addc_u32 s7, s7, 0
	global_load_dwordx2 v[90:91], v16, s[6:7]
	s_add_u32 s6, s6, 0x1000
	s_addc_u32 s7, s7, 0
	s_lshl_b32 s3, s2, 12
	s_add_u32 s6, s42, 0x2b700000
	s_addc_u32 s7, s43, 0
	s_add_u32 s6, s6, s3
	s_addc_u32 s7, s7, 0
	global_load_dwordx2 v[92:93], v16, s[6:7]
	s_add_u32 s8, s42, 0x2df00000
	s_addc_u32 s9, s43, 0
	s_add_u32 s8, s8, s3
	s_addc_u32 s9, s9, 0
	v_mov_b32_e32 v108, v202
	v_mov_b32_e32 v109, v203
	s_waitcnt vmcnt(0)
	v_pk_fma_f32 v[108:109], v[140:141], v[32:33], v[108:109]
	v_pk_fma_f32 v[108:109], v[142:143], v[34:35], v[108:109]
	v_pk_fma_f32 v[108:109], v[144:145], v[36:37], v[108:109]
	v_pk_fma_f32 v[108:109], v[146:147], v[38:39], v[108:109]
	v_pk_fma_f32 v[108:109], v[148:149], v[40:41], v[108:109]
	v_pk_fma_f32 v[108:109], v[150:151], v[42:43], v[108:109]
	v_pk_fma_f32 v[108:109], v[152:153], v[44:45], v[108:109]
	v_pk_fma_f32 v[108:109], v[154:155], v[46:47], v[108:109]
	v_pk_fma_f32 v[108:109], v[156:157], v[48:49], v[108:109]
	v_pk_fma_f32 v[108:109], v[158:159], v[50:51], v[108:109]
	v_pk_fma_f32 v[108:109], v[160:161], v[52:53], v[108:109]
	v_pk_fma_f32 v[108:109], v[162:163], v[54:55], v[108:109]
	v_pk_fma_f32 v[108:109], v[164:165], v[56:57], v[108:109]
	v_pk_fma_f32 v[108:109], v[166:167], v[58:59], v[108:109]
	v_pk_fma_f32 v[108:109], v[168:169], v[60:61], v[108:109]
	v_pk_fma_f32 v[108:109], v[170:171], v[62:63], v[108:109]
	v_pk_fma_f32 v[108:109], v[172:173], v[64:65], v[108:109]
	v_pk_fma_f32 v[108:109], v[174:175], v[66:67], v[108:109]
	v_pk_fma_f32 v[108:109], v[176:177], v[68:69], v[108:109]
	v_pk_fma_f32 v[108:109], v[178:179], v[70:71], v[108:109]
	v_pk_fma_f32 v[108:109], v[180:181], v[72:73], v[108:109]
	v_pk_fma_f32 v[108:109], v[182:183], v[74:75], v[108:109]
	v_pk_fma_f32 v[108:109], v[184:185], v[76:77], v[108:109]
	v_pk_fma_f32 v[108:109], v[186:187], v[78:79], v[108:109]
	v_pk_fma_f32 v[108:109], v[188:189], v[80:81], v[108:109]
	v_pk_fma_f32 v[108:109], v[190:191], v[82:83], v[108:109]
	v_pk_fma_f32 v[108:109], v[192:193], v[84:85], v[108:109]
	v_pk_fma_f32 v[108:109], v[194:195], v[86:87], v[108:109]
	v_pk_fma_f32 v[108:109], v[196:197], v[88:89], v[108:109]
	v_pk_fma_f32 v[108:109], v[198:199], v[90:91], v[108:109]
	v_pk_fma_f32 v[108:109], v[200:201], v[92:93], v[108:109]
	ds_write_b64 v16, v[108:109]
	s_waitcnt lgkmcnt(0)
	s_barrier
	v_readfirstlane_b32 s3, v230
	s_nop 3
	s_cmp_eq_u32 s3, 0
	s_cbranch_scc0 .Lcv_sample_b2
	ds_read_b128 v[8:11], v17 offset:0
	ds_read_b128 v[12:15], v17 offset:1024
	ds_read_b128 v[20:23], v17 offset:2048
	ds_read_b128 v[24:27], v17 offset:3072
	s_waitcnt lgkmcnt(0)
.Lcv_sample_b2:
	s_barrier
	s_cmp_eq_u32 s3, 0
	s_cbranch_scc0 .Lcv_nosample
	v_pk_add_f32 v[108:109], v[8:9], v[10:11]
	v_pk_add_f32 v[108:109], v[108:109], v[12:13]
	v_pk_add_f32 v[108:109], v[108:109], v[14:15]
	v_pk_add_f32 v[108:109], v[108:109], v[20:21]
	v_pk_add_f32 v[108:109], v[108:109], v[22:23]
	v_pk_add_f32 v[108:109], v[108:109], v[24:25]
	v_pk_add_f32 v[108:109], v[108:109], v[26:27]
	v_add_f32_e32 v108, v108, v109
	s_nop 1
	v_add_f32_dpp v108, v108, v108 quad_perm:[1,0,3,2] row_mask:0xf bank_mask:0xf bound_ctrl:1
	s_nop 1
	v_add_f32_dpp v108, v108, v108 quad_perm:[2,3,0,1] row_mask:0xf bank_mask:0xf bound_ctrl:1
	s_nop 1
	v_add_f32_dpp v108, v108, v108 row_half_mirror row_mask:0xf bank_mask:0xf bound_ctrl:1
	s_nop 1
	v_add_f32_dpp v108, v108, v108 row_mirror row_mask:0xf bank_mask:0xf bound_ctrl:1
	v_mov_b32_e32 v114, v108
	s_nop 1
	v_permlane16_swap_b32 v108, v114
	s_nop 0
	v_add_f32_e32 v108, v108, v114
	v_mov_b32_e32 v114, v108
	s_nop 1
	v_permlane32_swap_b32 v108, v114
	s_nop 0
	v_add_f32_e32 v108, v108, v114
	v_mul_f32_e32 v110, 0x3a800000, v108
	v_pk_add_f32 v[8:9], v[8:9], v[110:111] op_sel_hi:[1,0] neg_lo:[0,1] neg_hi:[0,1]
	v_pk_add_f32 v[10:11], v[10:11], v[110:111] op_sel_hi:[1,0] neg_lo:[0,1] neg_hi:[0,1]
	v_pk_add_f32 v[12:13], v[12:13], v[110:111] op_sel_hi:[1,0] neg_lo:[0,1] neg_hi:[0,1]
	v_pk_add_f32 v[14:15], v[14:15], v[110:111] op_sel_hi:[1,0] neg_lo:[0,1] neg_hi:[0,1]
	v_pk_add_f32 v[20:21], v[20:21], v[110:111] op_sel_hi:[1,0] neg_lo:[0,1] neg_hi:[0,1]
	v_pk_add_f32 v[22:23], v[22:23], v[110:111] op_sel_hi:[1,0] neg_lo:[0,1] neg_hi:[0,1]
	v_pk_add_f32 v[24:25], v[24:25], v[110:111] op_sel_hi:[1,0] neg_lo:[0,1] neg_hi:[0,1]
	v_pk_add_f32 v[26:27], v[26:27], v[110:111] op_sel_hi:[1,0] neg_lo:[0,1] neg_hi:[0,1]
	v_pk_mul_f32 v[108:109], v[8:9], v[8:9]
	v_pk_fma_f32 v[108:109], v[10:11], v[10:11], v[108:109]
	v_pk_fma_f32 v[108:109], v[12:13], v[12:13], v[108:109]
	v_pk_fma_f32 v[108:109], v[14:15], v[14:15], v[108:109]
	v_pk_fma_f32 v[108:109], v[20:21], v[20:21], v[108:109]
	v_pk_fma_f32 v[108:109], v[22:23], v[22:23], v[108:109]
	v_pk_fma_f32 v[108:109], v[24:25], v[24:25], v[108:109]
	v_pk_fma_f32 v[108:109], v[26:27], v[26:27], v[108:109]
	v_add_f32_e32 v108, v108, v109
	s_nop 1
	v_add_f32_dpp v108, v108, v108 quad_perm:[1,0,3,2] row_mask:0xf bank_mask:0xf bound_ctrl:1
	s_nop 1
	v_add_f32_dpp v108, v108, v108 quad_perm:[2,3,0,1] row_mask:0xf bank_mask:0xf bound_ctrl:1
	s_nop 1
	v_add_f32_dpp v108, v108, v108 row_half_mirror row_mask:0xf bank_mask:0xf bound_ctrl:1
	s_nop 1
	v_add_f32_dpp v108, v108, v108 row_mirror row_mask:0xf bank_mask:0xf bound_ctrl:1
	v_mov_b32_e32 v114, v108
	s_nop 1
	v_permlane16_swap_b32 v108, v114
	s_nop 0
	v_add_f32_e32 v108, v108, v114
	v_mov_b32_e32 v114, v108
	s_nop 1
	v_permlane32_swap_b32 v108, v114
	s_nop 0
	v_add_f32_e32 v108, v108, v114
	v_mul_f32_e32 v112, 0x3a800000, v108
	v_add_f32_e32 v112, 0x3727c5ac, v112
	v_rsq_f32_e32 v112, v112
	s_nop 0
	v_pk_mul_f32 v[116:117], v[204:205], v[112:113] op_sel_hi:[1,0]
	v_pk_fma_f32 v[8:9], v[8:9], v[116:117], v[240:241]
	v_pk_mul_f32 v[116:117], v[206:207], v[112:113] op_sel_hi:[1,0]
	v_pk_fma_f32 v[10:11], v[10:11], v[116:117], v[242:243]
	v_pk_mul_f32 v[116:117], v[208:209], v[112:113] op_sel_hi:[1,0]
	v_pk_fma_f32 v[12:13], v[12:13], v[116:117], v[244:245]
	v_pk_mul_f32 v[116:117], v[210:211], v[112:113] op_sel_hi:[1,0]
	v_pk_fma_f32 v[14:15], v[14:15], v[116:117], v[246:247]
	v_pk_mul_f32 v[116:117], v[212:213], v[112:113] op_sel_hi:[1,0]
	v_pk_fma_f32 v[20:21], v[20:21], v[116:117], v[248:249]
	v_pk_mul_f32 v[116:117], v[214:215], v[112:113] op_sel_hi:[1,0]
	v_pk_fma_f32 v[22:23], v[22:23], v[116:117], v[250:251]
	v_pk_mul_f32 v[116:117], v[216:217], v[112:113] op_sel_hi:[1,0]
	v_pk_fma_f32 v[24:25], v[24:25], v[116:117], v[124:125]
	v_pk_mul_f32 v[116:117], v[218:219], v[112:113] op_sel_hi:[1,0]
	v_pk_fma_f32 v[26:27], v[26:27], v[116:117], v[126:127]
	v_mul_f32_e32 v118, 0xbfb8aa3b, v8
	v_mul_f32_e32 v119, 0xbfb8aa3b, v9
	v_mul_f32_e32 v120, 0xbfb8aa3b, v10
	v_mul_f32_e32 v121, 0xbfb8aa3b, v11
	v_mul_f32_e32 v122, 0xbfb8aa3b, v12
	v_mul_f32_e32 v123, 0xbfb8aa3b, v13
	v_mul_f32_e32 v108, 0xbfb8aa3b, v14
	v_mul_f32_e32 v109, 0xbfb8aa3b, v15
	v_mul_f32_e32 v110, 0xbfb8aa3b, v20
	v_mul_f32_e32 v111, 0xbfb8aa3b, v21
	v_mul_f32_e32 v112, 0xbfb8aa3b, v22
	v_mul_f32_e32 v113, 0xbfb8aa3b, v23
	v_mul_f32_e32 v114, 0xbfb8aa3b, v24
	v_mul_f32_e32 v115, 0xbfb8aa3b, v25
	v_mul_f32_e32 v116, 0xbfb8aa3b, v26
	v_mul_f32_e32 v117, 0xbfb8aa3b, v27
	v_exp_f32_e32 v118, v118
	v_exp_f32_e32 v119, v119
	v_exp_f32_e32 v120, v120
	v_exp_f32_e32 v121, v121
	v_exp_f32_e32 v122, v122
	v_exp_f32_e32 v123, v123
	v_exp_f32_e32 v108, v108
	v_exp_f32_e32 v109, v109
	v_exp_f32_e32 v110, v110
	v_exp_f32_e32 v111, v111
	v_exp_f32_e32 v112, v112
	v_exp_f32_e32 v113, v113
	v_exp_f32_e32 v114, v114
	v_exp_f32_e32 v115, v115
	v_exp_f32_e32 v116, v116
	v_exp_f32_e32 v117, v117
	v_add_f32_e32 v118, 1.0, v118
	v_add_f32_e32 v119, 1.0, v119
	v_add_f32_e32 v120, 1.0, v120
	v_add_f32_e32 v121, 1.0, v121
	v_add_f32_e32 v122, 1.0, v122
	v_add_f32_e32 v123, 1.0, v123
	v_add_f32_e32 v108, 1.0, v108
	v_add_f32_e32 v109, 1.0, v109
	v_add_f32_e32 v110, 1.0, v110
	v_add_f32_e32 v111, 1.0, v111
	v_add_f32_e32 v112, 1.0, v112
	v_add_f32_e32 v113, 1.0, v113
	v_add_f32_e32 v114, 1.0, v114
	v_add_f32_e32 v115, 1.0, v115
	v_add_f32_e32 v116, 1.0, v116
	v_add_f32_e32 v117, 1.0, v117
	v_rcp_f32_e32 v118, v118
	v_rcp_f32_e32 v119, v119
	v_rcp_f32_e32 v120, v120
	v_rcp_f32_e32 v121, v121
	v_rcp_f32_e32 v122, v122
	v_rcp_f32_e32 v123, v123
	v_rcp_f32_e32 v108, v108
	v_rcp_f32_e32 v109, v109
	v_rcp_f32_e32 v110, v110
	v_rcp_f32_e32 v111, v111
	v_rcp_f32_e32 v112, v112
	v_rcp_f32_e32 v113, v113
	v_rcp_f32_e32 v114, v114
	v_rcp_f32_e32 v115, v115
	v_rcp_f32_e32 v116, v116
	v_rcp_f32_e32 v117, v117
	v_mul_f32_e32 v8, v8, v118
	v_mul_f32_e32 v9, v9, v119
	v_mul_f32_e32 v10, v10, v120
	v_mul_f32_e32 v11, v11, v121
	v_mul_f32_e32 v12, v12, v122
	v_mul_f32_e32 v13, v13, v123
	v_mul_f32_e32 v14, v14, v108
	v_mul_f32_e32 v15, v15, v109
	v_mul_f32_e32 v20, v20, v110
	v_mul_f32_e32 v21, v21, v111
	v_mul_f32_e32 v22, v22, v112
	v_mul_f32_e32 v23, v23, v113
	v_mul_f32_e32 v24, v24, v114
	v_mul_f32_e32 v25, v25, v115
	v_mul_f32_e32 v26, v26, v116
	v_mul_f32_e32 v27, v27, v117
	v_pk_mul_f32 v[8:9], v[8:9], v[128:129]
	v_pk_mul_f32 v[10:11], v[10:11], v[130:131]
	v_pk_mul_f32 v[12:13], v[12:13], v[132:133]
	v_pk_mul_f32 v[14:15], v[14:15], v[134:135]
	v_pk_mul_f32 v[20:21], v[20:21], v[0:1]
	v_pk_mul_f32 v[22:23], v[22:23], v[2:3]
	v_pk_mul_f32 v[24:25], v[24:25], v[4:5]
	v_pk_mul_f32 v[26:27], v[26:27], v[6:7]
	v_cvt_pk_bf16_f32 v8, v8, v9
	v_cvt_pk_bf16_f32 v9, v10, v11
	v_cvt_pk_bf16_f32 v12, v12, v13
	v_cvt_pk_bf16_f32 v13, v14, v15
	v_cvt_pk_bf16_f32 v20, v20, v21
	v_cvt_pk_bf16_f32 v21, v22, v23
	v_cvt_pk_bf16_f32 v24, v24, v25
	v_cvt_pk_bf16_f32 v25, v26, v27
	global_store_dwordx2 v19, v[8:9], s[8:9] offset:0
	global_store_dwordx2 v19, v[12:13], s[8:9] offset:512
	global_store_dwordx2 v19, v[20:21], s[8:9] offset:1024
	global_store_dwordx2 v19, v[24:25], s[8:9] offset:1536
.Lcv_nosample:
	s_waitcnt vmcnt(0)
	v_lshrrev_b32_e32 v1, 3, v136
	v_lshl_or_b32 v1, v230, 3, v1
	v_and_b32_e32 v2, 7, v231
	v_mov_b32_e32 v67, 0
	v_lshlrev_b32_e32 v66, 8, v1
	v_cmp_eq_u32_e64 s[6:7], 0, v2
	v_lshlrev_b32_e32 v2, 5, v2
	v_lshl_add_u64 v[10:11], s[72:73], 0, v[66:67]
	v_mov_b32_e32 v3, v67
	v_lshl_add_u64 v[68:69], v[10:11], 0, v[2:3]
	v_lshl_add_u64 v[10:11], s[40:41], 0, v[66:67]
	v_add_u32_e32 v137, 0, v2
	v_lshl_add_u64 v[2:3], v[10:11], 0, v[2:3]
	s_mov_b64 s[8:9], 0x6329200
	v_lshlrev_b32_e32 v66, 3, v231
	v_lshl_add_u64 v[70:71], v[2:3], 0, s[8:9]
	v_lshl_add_u64 v[72:73], s[22:23], 0, v[66:67]
	s_mov_b64 s[8:9], 0x1000
	v_lshl_add_u64 v[74:75], v[72:73], 0, s[8:9]
	s_mov_b64 s[8:9], 0x2000
	v_lshl_add_u64 v[76:77], v[72:73], 0, s[8:9]
	s_mov_b64 s[8:9], 0x3000
	v_lshl_add_u64 v[78:79], v[72:73], 0, s[8:9]
	s_mov_b64 s[8:9], 0x4000
	v_lshl_add_u64 v[80:81], v[72:73], 0, s[8:9]
	s_mov_b64 s[8:9], 0x5000
	v_lshl_add_u64 v[82:83], v[72:73], 0, s[8:9]
	s_mov_b64 s[8:9], 0x6000
	v_lshl_add_u64 v[84:85], v[72:73], 0, s[8:9]
	s_mov_b64 s[8:9], 0x7000
	v_lshl_add_u64 v[86:87], v[72:73], 0, s[8:9]
	s_mov_b64 s[8:9], 0x8000
	v_lshl_add_u64 v[88:89], v[72:73], 0, s[8:9]
	s_mov_b64 s[8:9], 0x9000
	v_lshl_add_u64 v[90:91], v[72:73], 0, s[8:9]
	s_mov_b64 s[8:9], 0xa000
	v_lshl_add_u64 v[92:93], v[72:73], 0, s[8:9]
	s_mov_b64 s[8:9], 0xb000
	v_lshl_add_u64 v[94:95], v[72:73], 0, s[8:9]
	s_mov_b64 s[8:9], 0xc000
	v_lshl_add_u64 v[96:97], v[72:73], 0, s[8:9]
	s_mov_b64 s[8:9], 0xd000
	v_lshl_add_u64 v[98:99], v[72:73], 0, s[8:9]
	s_mov_b64 s[8:9], 0xe000
	v_lshl_add_u64 v[100:101], v[72:73], 0, s[8:9]
	s_mov_b64 s[8:9], 0xf000
	v_lshl_add_u64 v[102:103], v[72:73], 0, s[8:9]
	s_mov_b64 s[8:9], 0x10000
	v_lshl_add_u64 v[104:105], v[72:73], 0, s[8:9]
	s_mov_b64 s[8:9], 0x11000
	v_lshl_add_u64 v[106:107], v[72:73], 0, s[8:9]
	s_mov_b64 s[8:9], 0x12000
	v_lshl_add_u64 v[108:109], v[72:73], 0, s[8:9]
	s_mov_b64 s[8:9], 0x13000
	v_lshl_add_u64 v[110:111], v[72:73], 0, s[8:9]
	s_mov_b64 s[8:9], 0x14000
	v_lshl_add_u64 v[112:113], v[72:73], 0, s[8:9]
	s_mov_b64 s[8:9], 0x15000
	v_lshl_add_u64 v[114:115], v[72:73], 0, s[8:9]
	s_mov_b64 s[8:9], 0x16000
	v_lshl_add_u64 v[116:117], v[72:73], 0, s[8:9]
	s_mov_b64 s[8:9], 0x17000
	v_lshl_add_u64 v[118:119], v[72:73], 0, s[8:9]
	s_mov_b64 s[8:9], 0x18000
	s_add_u32 s68, s42, 0x1d300000
	v_lshl_add_u64 v[120:121], v[72:73], 0, s[8:9]
	s_mov_b64 s[8:9], 0x19000
	s_addc_u32 s69, s43, 0
	v_lshl_add_u64 v[122:123], v[72:73], 0, s[8:9]
	s_mov_b64 s[8:9], 0x1a000
	s_add_u32 s40, s42, 0x1f380800
	v_lshl_add_u64 v[124:125], v[72:73], 0, s[8:9]
	s_mov_b64 s[8:9], 0x1b000
	s_addc_u32 s41, s43, 0
	v_lshl_add_u64 v[126:127], v[72:73], 0, s[8:9]
	s_mov_b64 s[8:9], 0x1c000
	v_lshlrev_b32_e32 v0, 4, v136
	v_lshl_add_u32 v240, v1, 2, 0
	v_lshl_add_u64 v[128:129], v[72:73], 0, s[8:9]
	s_mov_b64 s[8:9], 0x1d000
	s_add_u32 s22, s42, 0x29700000
	v_mov_b32_e32 v1, v67
	v_add_u32_e32 v5, 0, v0
	v_lshlrev_b32_e32 v7, 12, v230
	v_or_b32_e32 v4, 64, v136
	v_or_b32_e32 v6, 0x80, v136
	v_or_b32_e32 v8, 0xc0, v136
	v_lshl_add_u64 v[130:131], v[72:73], 0, s[8:9]
	s_mov_b64 s[8:9], 0x1e000
	s_addc_u32 s23, s43, 0
	v_lshl_add_u64 v[134:135], s[24:25], 0, v[66:67]
	v_lshl_add_u64 v[142:143], s[26:27], 0, v[0:1]
	v_lshl_add_u64 v[144:145], s[36:37], 0, v[0:1]
	v_lshl_add_u64 v[146:147], s[70:71], 0, v[0:1]
	s_lshl_b32 s3, s2, 15
	v_mov_b32_e32 v0, 0xfff70000
	s_mov_b32 s24, 0xf9700000
	s_mov_b32 s67, 0
	v_add_u32_e32 v65, 0, v138
	v_lshlrev_b32_e32 v64, 1, v231
	v_lshl_add_u64 v[132:133], v[72:73], 0, s[8:9]
	v_lshl_add_u64 v[140:141], s[22:23], 0, v[66:67]
	s_add_i32 s66, s3, 0xfdc00000
	s_lshl_b32 s3, s34, 15
	v_lshl_add_u32 v241, v18, 6, v0
	s_lshl_b32 s83, s34, 9
	s_sub_i32 s84, s74, 30
	s_lshl_b32 s85, s34, 3
	s_movk_i32 s86, 0x2000
	s_movk_i32 s87, 0x3c0
	s_movk_i32 s88, 0xd20
	s_mov_b32 s25, -1
	s_mov_b32 s89, 0xf800000
	v_mov_b32_e32 v242, 0x260
	v_mov_b32_e32 v243, 0x3a27c5ac
	v_add_u32_e32 v244, v5, v7
	v_mov_b32_e32 v245, 0x3727c5ac
	s_mov_b64 s[26:27], 0x2bf00800
	s_mov_b32 s90, 0xbfb8aa3b
	s_mov_b32 s91, 0x42ce8ed0
	s_mov_b32 s92, 0xc2b17218
	v_lshlrev_b32_e32 v148, 3, v4
	v_lshlrev_b32_e32 v150, 3, v6
	v_lshlrev_b32_e32 v152, 3, v8
	v_mov_b32_e32 v246, 0x7f800000
	s_mov_b32 s93, s2
	s_cmp_lt_u32 s2, 0x80
	s_cselect_b32 s76, 5, 4
	s_mul_i32 s75, s34, s76
	s_add_i32 s93, s93, s75
	s_mul_i32 s75, s3, s76
	s_add_i32 s66, s66, s75
	s_mul_i32 s75, s85, s76
	s_add_i32 s84, s84, s75
	s_mul_i32 s75, s83, s76
	v_add_u32_e32 v241, s75, v241
	s_branch .LBB0_1309
